# GEMM main loops: the M0 wait-state pad before each segment's second LDS-DMA load is filled by the segment's last fragment read instead of s_nop
# baseline (speedup 1.0000x reference)
.LBB0_227:
	ds_read_b128 v[140:143], v234
	ds_read_b128 v[144:147], v234 offset:1024
	ds_read_b128 v[148:151], v234 offset:2048
	ds_read_b128 v[170:173], v234 offset:3072
	ds_read_b128 v[174:177], v168
	ds_read_b128 v[178:181], v168 offset:1024
	ds_read_b128 v[182:185], v168 offset:2048
	ds_read_b128 v[186:189], v168 offset:3072
	ds_read_b128 v[190:193], v168 offset:4096
	ds_read_b128 v[206:209], v168 offset:5120
	ds_read_b128 v[210:213], v168 offset:6144
	global_load_lds_dwordx4 v136, s[20:21]
	s_add_i32 m0, s49, 0xe000
	ds_read_b128 v[214:217], v168 offset:7168
	global_load_lds_dwordx4 v138, s[20:21]
	s_waitcnt lgkmcnt(8)
	s_barrier
	s_waitcnt lgkmcnt(0)
	v_mfma_f32_16x16x32_bf16 v[124:127], v[140:143], v[174:177], v[124:127]
	v_mfma_f32_16x16x32_bf16 v[120:123], v[148:151], v[174:177], v[120:123]
	v_mfma_f32_16x16x32_bf16 v[108:111], v[140:143], v[182:185], v[108:111]
	v_mfma_f32_16x16x32_bf16 v[104:107], v[148:151], v[182:185], v[104:107]
	v_mfma_f32_16x16x32_bf16 v[92:95], v[140:143], v[190:193], v[92:95]
	v_mfma_f32_16x16x32_bf16 v[88:91], v[148:151], v[190:193], v[88:91]
	v_mfma_f32_16x16x32_bf16 v[76:79], v[140:143], v[210:213], v[76:79]
	v_mfma_f32_16x16x32_bf16 v[72:75], v[148:151], v[210:213], v[72:75]
	v_mfma_f32_16x16x32_bf16 v[124:127], v[144:147], v[178:181], v[124:127]
	v_mfma_f32_16x16x32_bf16 v[120:123], v[170:173], v[178:181], v[120:123]
	v_mfma_f32_16x16x32_bf16 v[108:111], v[144:147], v[186:189], v[108:111]
	v_mfma_f32_16x16x32_bf16 v[104:107], v[170:173], v[186:189], v[104:107]
	v_mfma_f32_16x16x32_bf16 v[92:95], v[144:147], v[206:209], v[92:95]
	v_mfma_f32_16x16x32_bf16 v[88:91], v[170:173], v[206:209], v[88:91]
	v_mfma_f32_16x16x32_bf16 v[76:79], v[144:147], v[214:217], v[76:79]
	v_mfma_f32_16x16x32_bf16 v[72:75], v[170:173], v[214:217], v[72:75]
	s_barrier
	s_add_i32 s62, 0, 0x14000
	s_add_i32 s59, s59, s48
	s_mov_b32 m0, s59
	ds_read_b128 v[218:221], v235
	ds_read_b128 v[222:225], v235 offset:1024
	ds_read_b128 v[226:229], v235 offset:2048
	global_load_lds_dwordx4 v130, s[22:23]
	s_add_i32 m0, s59, 0x2000
	ds_read_b128 v[230:233], v235 offset:3072
	global_load_lds_dwordx4 v134, s[22:23]
	s_barrier
	s_waitcnt lgkmcnt(0)
	v_mfma_f32_16x16x32_bf16 v[116:119], v[218:221], v[174:177], v[116:119]
	v_mfma_f32_16x16x32_bf16 v[112:115], v[226:229], v[174:177], v[112:115]
	v_mfma_f32_16x16x32_bf16 v[100:103], v[218:221], v[182:185], v[100:103]
	v_mfma_f32_16x16x32_bf16 v[96:99], v[226:229], v[182:185], v[96:99]
	v_mfma_f32_16x16x32_bf16 v[84:87], v[218:221], v[190:193], v[84:87]
	v_mfma_f32_16x16x32_bf16 v[80:83], v[226:229], v[190:193], v[80:83]
	v_mfma_f32_16x16x32_bf16 v[68:71], v[218:221], v[210:213], v[68:71]
	v_mfma_f32_16x16x32_bf16 v[64:67], v[226:229], v[210:213], v[64:67]
	v_mfma_f32_16x16x32_bf16 v[116:119], v[222:225], v[178:181], v[116:119]
	v_mfma_f32_16x16x32_bf16 v[112:115], v[230:233], v[178:181], v[112:115]
	v_mfma_f32_16x16x32_bf16 v[100:103], v[222:225], v[186:189], v[100:103]
	v_mfma_f32_16x16x32_bf16 v[96:99], v[230:233], v[186:189], v[96:99]
	v_mfma_f32_16x16x32_bf16 v[84:87], v[222:225], v[206:209], v[84:87]
	v_mfma_f32_16x16x32_bf16 v[80:83], v[230:233], v[206:209], v[80:83]
	v_mfma_f32_16x16x32_bf16 v[68:71], v[222:225], v[214:217], v[68:71]
	v_mfma_f32_16x16x32_bf16 v[64:67], v[230:233], v[214:217], v[64:67]
	s_barrier
	s_mov_b32 m0, s49
	s_add_u32 s98, s42, 0x80
	s_addc_u32 s99, s43, 0
	ds_read_b128 v[174:177], v168 offset:16384
	ds_read_b128 v[178:181], v168 offset:17408
	ds_read_b128 v[182:185], v168 offset:18432
	ds_read_b128 v[186:189], v168 offset:19456
	ds_read_b128 v[190:193], v168 offset:20480
	ds_read_b128 v[206:209], v168 offset:21504
	ds_read_b128 v[210:213], v168 offset:22528
	global_load_lds_dwordx4 v128, s[42:43]
	s_mov_b32 m0, s50
	ds_read_b128 v[214:217], v168 offset:23552
	global_load_lds_dwordx4 v132, s[42:43]
	s_barrier
	s_waitcnt lgkmcnt(0)
	v_mfma_f32_16x16x32_bf16 v[60:63], v[140:143], v[174:177], v[60:63]
	v_mfma_f32_16x16x32_bf16 v[56:59], v[148:151], v[174:177], v[56:59]
	v_mfma_f32_16x16x32_bf16 v[48:51], v[140:143], v[182:185], v[48:51]
	v_mfma_f32_16x16x32_bf16 v[40:43], v[148:151], v[182:185], v[40:43]
	v_mfma_f32_16x16x32_bf16 v[32:35], v[140:143], v[190:193], v[32:35]
	v_mfma_f32_16x16x32_bf16 v[24:27], v[148:151], v[190:193], v[24:27]
	v_mfma_f32_16x16x32_bf16 v[16:19], v[140:143], v[210:213], v[16:19]
	v_mfma_f32_16x16x32_bf16 v[8:11], v[148:151], v[210:213], v[8:11]
	v_mfma_f32_16x16x32_bf16 v[60:63], v[144:147], v[178:181], v[60:63]
	v_mfma_f32_16x16x32_bf16 v[56:59], v[170:173], v[178:181], v[56:59]
	v_mfma_f32_16x16x32_bf16 v[48:51], v[144:147], v[186:189], v[48:51]
	v_mfma_f32_16x16x32_bf16 v[40:43], v[170:173], v[186:189], v[40:43]
	v_mfma_f32_16x16x32_bf16 v[32:35], v[144:147], v[206:209], v[32:35]
	v_mfma_f32_16x16x32_bf16 v[24:27], v[170:173], v[206:209], v[24:27]
	v_mfma_f32_16x16x32_bf16 v[16:19], v[144:147], v[214:217], v[16:19]
	v_mfma_f32_16x16x32_bf16 v[8:11], v[170:173], v[214:217], v[8:11]
	s_barrier
	s_add_u32 s60, s22, 0x80000
	s_addc_u32 s61, s23, 0
	s_add_i32 s59, s62, s48
	s_mov_b32 m0, s59
	s_nop 0
	global_load_lds_dwordx4 v130, s[60:61]
	s_add_i32 m0, s59, 0x2000
	s_nop 0
	global_load_lds_dwordx4 v134, s[60:61]
	s_add_i32 s59, 0, 0x18000
	s_add_u32 s42, s42, 0x80000
	s_addc_u32 s43, s43, 0
	s_mov_b32 m0, s51
	s_waitcnt vmcnt(6)
	s_barrier
	v_mfma_f32_16x16x32_bf16 v[52:55], v[218:221], v[174:177], v[52:55]
	v_mfma_f32_16x16x32_bf16 v[44:47], v[226:229], v[174:177], v[44:47]
	v_mfma_f32_16x16x32_bf16 v[36:39], v[218:221], v[182:185], v[36:39]
	v_mfma_f32_16x16x32_bf16 v[28:31], v[226:229], v[182:185], v[28:31]
	v_mfma_f32_16x16x32_bf16 v[20:23], v[218:221], v[190:193], v[20:23]
	v_mfma_f32_16x16x32_bf16 v[12:15], v[226:229], v[190:193], v[12:15]
	v_mfma_f32_16x16x32_bf16 v[4:7], v[218:221], v[210:213], v[4:7]
	v_mfma_f32_16x16x32_bf16 v[0:3], v[226:229], v[210:213], v[0:3]
	v_mfma_f32_16x16x32_bf16 v[52:55], v[222:225], v[178:181], v[52:55]
	v_mfma_f32_16x16x32_bf16 v[44:47], v[230:233], v[178:181], v[44:47]
	v_mfma_f32_16x16x32_bf16 v[36:39], v[222:225], v[186:189], v[36:39]
	v_mfma_f32_16x16x32_bf16 v[28:31], v[230:233], v[186:189], v[28:31]
	v_mfma_f32_16x16x32_bf16 v[20:23], v[222:225], v[206:209], v[20:23]
	v_mfma_f32_16x16x32_bf16 v[12:15], v[230:233], v[206:209], v[12:15]
	v_mfma_f32_16x16x32_bf16 v[4:7], v[222:225], v[214:217], v[4:7]
	v_mfma_f32_16x16x32_bf16 v[0:3], v[230:233], v[214:217], v[0:3]
	s_barrier
	ds_read_b128 v[140:143], v236
	ds_read_b128 v[144:147], v236 offset:1024
	ds_read_b128 v[148:151], v236 offset:2048
	ds_read_b128 v[170:173], v236 offset:3072
	ds_read_b128 v[174:177], v168 offset:32768
	ds_read_b128 v[178:181], v168 offset:33792
	ds_read_b128 v[182:185], v168 offset:34816
	ds_read_b128 v[186:189], v168 offset:35840
	ds_read_b128 v[190:193], v168 offset:36864
	ds_read_b128 v[206:209], v168 offset:37888
	ds_read_b128 v[210:213], v168 offset:38912
	global_load_lds_dwordx4 v128, s[42:43]
	s_mov_b32 m0, s52
	ds_read_b128 v[214:217], v168 offset:39936
	global_load_lds_dwordx4 v132, s[42:43]
	s_waitcnt lgkmcnt(8)
	s_barrier
	s_waitcnt lgkmcnt(0)
	v_mfma_f32_16x16x32_bf16 v[124:127], v[140:143], v[174:177], v[124:127]
	v_mfma_f32_16x16x32_bf16 v[120:123], v[148:151], v[174:177], v[120:123]
	v_mfma_f32_16x16x32_bf16 v[108:111], v[140:143], v[182:185], v[108:111]
	v_mfma_f32_16x16x32_bf16 v[104:107], v[148:151], v[182:185], v[104:107]
	v_mfma_f32_16x16x32_bf16 v[92:95], v[140:143], v[190:193], v[92:95]
	v_mfma_f32_16x16x32_bf16 v[88:91], v[148:151], v[190:193], v[88:91]
	v_mfma_f32_16x16x32_bf16 v[76:79], v[140:143], v[210:213], v[76:79]
	v_mfma_f32_16x16x32_bf16 v[72:75], v[148:151], v[210:213], v[72:75]
	v_mfma_f32_16x16x32_bf16 v[124:127], v[144:147], v[178:181], v[124:127]
	v_mfma_f32_16x16x32_bf16 v[120:123], v[170:173], v[178:181], v[120:123]
	v_mfma_f32_16x16x32_bf16 v[108:111], v[144:147], v[186:189], v[108:111]
	v_mfma_f32_16x16x32_bf16 v[104:107], v[170:173], v[186:189], v[104:107]
	v_mfma_f32_16x16x32_bf16 v[92:95], v[144:147], v[206:209], v[92:95]
	v_mfma_f32_16x16x32_bf16 v[88:91], v[170:173], v[206:209], v[88:91]
	v_mfma_f32_16x16x32_bf16 v[76:79], v[144:147], v[214:217], v[76:79]
	v_mfma_f32_16x16x32_bf16 v[72:75], v[170:173], v[214:217], v[72:75]
	s_barrier
	s_add_i32 s42, 0, 0x1c000
	s_add_i32 s43, s59, s48
	s_add_u32 s100, s22, 0x80
	s_addc_u32 s101, s23, 0
	s_mov_b32 m0, s43
	ds_read_b128 v[218:221], v237
	ds_read_b128 v[222:225], v237 offset:1024
	ds_read_b128 v[226:229], v237 offset:2048
	global_load_lds_dwordx4 v130, s[100:101]
	s_add_i32 m0, s43, 0x2000
	ds_read_b128 v[230:233], v237 offset:3072
	global_load_lds_dwordx4 v134, s[100:101]
	s_barrier
	s_waitcnt lgkmcnt(0)
	v_mfma_f32_16x16x32_bf16 v[116:119], v[218:221], v[174:177], v[116:119]
	v_mfma_f32_16x16x32_bf16 v[112:115], v[226:229], v[174:177], v[112:115]
	v_mfma_f32_16x16x32_bf16 v[100:103], v[218:221], v[182:185], v[100:103]
	v_mfma_f32_16x16x32_bf16 v[96:99], v[226:229], v[182:185], v[96:99]
	v_mfma_f32_16x16x32_bf16 v[84:87], v[218:221], v[190:193], v[84:87]
	v_mfma_f32_16x16x32_bf16 v[80:83], v[226:229], v[190:193], v[80:83]
	v_mfma_f32_16x16x32_bf16 v[68:71], v[218:221], v[210:213], v[68:71]
	v_mfma_f32_16x16x32_bf16 v[64:67], v[226:229], v[210:213], v[64:67]
	v_mfma_f32_16x16x32_bf16 v[116:119], v[222:225], v[178:181], v[116:119]
	v_mfma_f32_16x16x32_bf16 v[112:115], v[230:233], v[178:181], v[112:115]
	v_mfma_f32_16x16x32_bf16 v[100:103], v[222:225], v[186:189], v[100:103]
	v_mfma_f32_16x16x32_bf16 v[96:99], v[230:233], v[186:189], v[96:99]
	v_mfma_f32_16x16x32_bf16 v[84:87], v[222:225], v[206:209], v[84:87]
	v_mfma_f32_16x16x32_bf16 v[80:83], v[230:233], v[206:209], v[80:83]
	v_mfma_f32_16x16x32_bf16 v[68:71], v[222:225], v[214:217], v[68:71]
	v_mfma_f32_16x16x32_bf16 v[64:67], v[230:233], v[214:217], v[64:67]
	s_barrier
	s_mov_b32 m0, s53
	ds_read_b128 v[174:177], v168 offset:49152
	ds_read_b128 v[178:181], v168 offset:50176
	ds_read_b128 v[182:185], v168 offset:51200
	ds_read_b128 v[186:189], v168 offset:52224
	ds_read_b128 v[190:193], v168 offset:53248
	ds_read_b128 v[206:209], v168 offset:54272
	ds_read_b128 v[210:213], v168 offset:55296
	global_load_lds_dwordx4 v128, s[98:99]
	s_mov_b32 m0, s54
	ds_read_b128 v[214:217], v168 offset:56320
	global_load_lds_dwordx4 v132, s[98:99]
	s_barrier
	s_waitcnt lgkmcnt(0)
	v_mfma_f32_16x16x32_bf16 v[60:63], v[140:143], v[174:177], v[60:63]
	v_mfma_f32_16x16x32_bf16 v[56:59], v[148:151], v[174:177], v[56:59]
	v_mfma_f32_16x16x32_bf16 v[48:51], v[140:143], v[182:185], v[48:51]
	v_mfma_f32_16x16x32_bf16 v[40:43], v[148:151], v[182:185], v[40:43]
	v_mfma_f32_16x16x32_bf16 v[32:35], v[140:143], v[190:193], v[32:35]
	v_mfma_f32_16x16x32_bf16 v[24:27], v[148:151], v[190:193], v[24:27]
	v_mfma_f32_16x16x32_bf16 v[16:19], v[140:143], v[210:213], v[16:19]
	v_mfma_f32_16x16x32_bf16 v[8:11], v[148:151], v[210:213], v[8:11]
	v_mfma_f32_16x16x32_bf16 v[60:63], v[144:147], v[178:181], v[60:63]
	v_mfma_f32_16x16x32_bf16 v[56:59], v[170:173], v[178:181], v[56:59]
	v_mfma_f32_16x16x32_bf16 v[48:51], v[144:147], v[186:189], v[48:51]
	v_mfma_f32_16x16x32_bf16 v[40:43], v[170:173], v[186:189], v[40:43]
	v_mfma_f32_16x16x32_bf16 v[32:35], v[144:147], v[206:209], v[32:35]
	v_mfma_f32_16x16x32_bf16 v[24:27], v[170:173], v[206:209], v[24:27]
	v_mfma_f32_16x16x32_bf16 v[16:19], v[144:147], v[214:217], v[16:19]
	v_mfma_f32_16x16x32_bf16 v[8:11], v[170:173], v[214:217], v[8:11]
	s_barrier
	s_add_u32 s22, s22, 0x80080
	s_addc_u32 s23, s23, 0
	s_add_i32 s42, s42, s48
	s_mov_b32 m0, s42
	s_nop 0
	global_load_lds_dwordx4 v130, s[22:23]
	s_add_i32 m0, s42, 0x2000
	s_nop 0
	global_load_lds_dwordx4 v134, s[22:23]
	s_add_i32 s58, s58, 2
	s_add_u32 s20, s20, 0x100
	s_addc_u32 s21, s21, 0
	s_add_u32 s35, s35, 0x100
	s_addc_u32 s57, s57, 0
	s_add_u32 s22, s20, 0xfff80080
	s_addc_u32 s23, s21, -1
	s_add_i32 s59, 0, 0x10000
	s_cmp_eq_u32 s58, 28
	s_cselect_b32 s43, s5, s23
	s_cselect_b32 s42, s6, s22
	s_cselect_b32 s23, s7, s57
	s_cselect_b32 s22, s25, s35
	s_add_i32 m0, s49, 0xc000
	s_cmp_gt_u32 s58, 29
	s_waitcnt vmcnt(6)
	s_barrier
	v_mfma_f32_16x16x32_bf16 v[52:55], v[218:221], v[174:177], v[52:55]
	v_mfma_f32_16x16x32_bf16 v[44:47], v[226:229], v[174:177], v[44:47]
	v_mfma_f32_16x16x32_bf16 v[36:39], v[218:221], v[182:185], v[36:39]
	v_mfma_f32_16x16x32_bf16 v[28:31], v[226:229], v[182:185], v[28:31]
	v_mfma_f32_16x16x32_bf16 v[20:23], v[218:221], v[190:193], v[20:23]
	v_mfma_f32_16x16x32_bf16 v[12:15], v[226:229], v[190:193], v[12:15]
	v_mfma_f32_16x16x32_bf16 v[4:7], v[218:221], v[210:213], v[4:7]
	v_mfma_f32_16x16x32_bf16 v[0:3], v[226:229], v[210:213], v[0:3]
	v_mfma_f32_16x16x32_bf16 v[52:55], v[222:225], v[178:181], v[52:55]
	v_mfma_f32_16x16x32_bf16 v[44:47], v[230:233], v[178:181], v[44:47]
	v_mfma_f32_16x16x32_bf16 v[36:39], v[222:225], v[186:189], v[36:39]
	v_mfma_f32_16x16x32_bf16 v[28:31], v[230:233], v[186:189], v[28:31]
	v_mfma_f32_16x16x32_bf16 v[20:23], v[222:225], v[206:209], v[20:23]
	v_mfma_f32_16x16x32_bf16 v[12:15], v[230:233], v[206:209], v[12:15]
	v_mfma_f32_16x16x32_bf16 v[4:7], v[222:225], v[214:217], v[4:7]
	v_mfma_f32_16x16x32_bf16 v[0:3], v[230:233], v[214:217], v[0:3]
	s_barrier
	s_cbranch_scc0 .LBB0_227
	s_cmpk_gt_u32 s14, 0xff
	s_cbranch_scc1 .Lal_e0_p
	s_barrier

.LBB0_561:
	ds_read_b128 v[72:75], v246
	ds_read_b128 v[76:79], v246 offset:1024
	ds_read_b128 v[84:87], v246 offset:2048
	ds_read_b128 v[92:95], v246 offset:3072
	ds_read_b128 v[144:147], v208
	ds_read_b128 v[148:151], v208 offset:1024
	ds_read_b128 v[188:191], v208 offset:2048
	ds_read_b128 v[210:213], v208 offset:3072
	ds_read_b128 v[214:217], v208 offset:4096
	ds_read_b128 v[218:221], v208 offset:5120
	ds_read_b128 v[222:225], v208 offset:6144
	global_load_lds_dwordx4 v184, s[22:23]
	s_add_i32 m0, s61, 0xe000
	ds_read_b128 v[226:229], v208 offset:7168
	global_load_lds_dwordx4 v186, s[22:23]
	s_waitcnt lgkmcnt(8)
	s_barrier
	s_waitcnt lgkmcnt(0)
	v_mfma_f32_16x16x32_bf16 v[140:143], v[72:75], v[144:147], v[140:143]
	v_mfma_f32_16x16x32_bf16 v[136:139], v[84:87], v[144:147], v[136:139]
	v_mfma_f32_16x16x32_bf16 v[124:127], v[72:75], v[188:191], v[124:127]
	v_mfma_f32_16x16x32_bf16 v[120:123], v[84:87], v[188:191], v[120:123]
	v_mfma_f32_16x16x32_bf16 v[108:111], v[72:75], v[214:217], v[108:111]
	v_mfma_f32_16x16x32_bf16 v[104:107], v[84:87], v[214:217], v[104:107]
	v_mfma_f32_16x16x32_bf16 v[88:91], v[72:75], v[222:225], v[88:91]
	v_mfma_f32_16x16x32_bf16 v[80:83], v[84:87], v[222:225], v[80:83]
	v_mfma_f32_16x16x32_bf16 v[140:143], v[76:79], v[148:151], v[140:143]
	v_mfma_f32_16x16x32_bf16 v[136:139], v[92:95], v[148:151], v[136:139]
	v_mfma_f32_16x16x32_bf16 v[124:127], v[76:79], v[210:213], v[124:127]
	v_mfma_f32_16x16x32_bf16 v[120:123], v[92:95], v[210:213], v[120:123]
	v_mfma_f32_16x16x32_bf16 v[108:111], v[76:79], v[218:221], v[108:111]
	v_mfma_f32_16x16x32_bf16 v[104:107], v[92:95], v[218:221], v[104:107]
	v_mfma_f32_16x16x32_bf16 v[88:91], v[76:79], v[226:229], v[88:91]
	v_mfma_f32_16x16x32_bf16 v[80:83], v[92:95], v[226:229], v[80:83]
	s_barrier
	s_add_i32 s86, 0, 0x14000
	s_add_i32 s84, s84, s60
	ds_read_b128 v[230:233], v247
	ds_read_b128 v[234:237], v247 offset:1024
	ds_read_b128 v[238:241], v247 offset:2048
	ds_read_b128 v[242:245], v247 offset:3072
	s_mov_b32 m0, s84
	s_nop 0
	global_load_lds_dwordx4 v152, s[38:39]
	s_add_i32 m0, s84, 0x2000
	s_nop 0
	global_load_lds_dwordx4 v162, s[38:39]
	s_barrier
	s_waitcnt lgkmcnt(0)
	v_mfma_f32_16x16x32_bf16 v[132:135], v[230:233], v[144:147], v[132:135]
	v_mfma_f32_16x16x32_bf16 v[128:131], v[238:241], v[144:147], v[128:131]
	v_mfma_f32_16x16x32_bf16 v[116:119], v[230:233], v[188:191], v[116:119]
	v_mfma_f32_16x16x32_bf16 v[112:115], v[238:241], v[188:191], v[112:115]
	v_mfma_f32_16x16x32_bf16 v[100:103], v[230:233], v[214:217], v[100:103]
	v_mfma_f32_16x16x32_bf16 v[96:99], v[238:241], v[214:217], v[96:99]
	v_mfma_f32_16x16x32_bf16 v[68:71], v[230:233], v[222:225], v[68:71]
	v_mfma_f32_16x16x32_bf16 v[64:67], v[238:241], v[222:225], v[64:67]
	v_mfma_f32_16x16x32_bf16 v[132:135], v[234:237], v[148:151], v[132:135]
	v_mfma_f32_16x16x32_bf16 v[128:131], v[242:245], v[148:151], v[128:131]
	v_mfma_f32_16x16x32_bf16 v[116:119], v[234:237], v[210:213], v[116:119]
	v_mfma_f32_16x16x32_bf16 v[112:115], v[242:245], v[210:213], v[112:115]
	v_mfma_f32_16x16x32_bf16 v[100:103], v[234:237], v[218:221], v[100:103]
	v_mfma_f32_16x16x32_bf16 v[96:99], v[242:245], v[218:221], v[96:99]
	v_mfma_f32_16x16x32_bf16 v[68:71], v[234:237], v[226:229], v[68:71]
	v_mfma_f32_16x16x32_bf16 v[64:67], v[242:245], v[226:229], v[64:67]
	s_barrier
	s_mov_b32 m0, s61
	s_add_u32 s98, s52, 0x80
	s_addc_u32 s99, s53, 0
	ds_read_b128 v[144:147], v208 offset:16384
	ds_read_b128 v[148:151], v208 offset:17408
	ds_read_b128 v[188:191], v208 offset:18432
	ds_read_b128 v[210:213], v208 offset:19456
	ds_read_b128 v[214:217], v208 offset:20480
	ds_read_b128 v[218:221], v208 offset:21504
	ds_read_b128 v[222:225], v208 offset:22528
	global_load_lds_dwordx4 v166, s[52:53]
	s_mov_b32 m0, s62
	ds_read_b128 v[226:229], v208 offset:23552
	global_load_lds_dwordx4 v164, s[52:53]
	s_barrier
	s_waitcnt lgkmcnt(0)
	v_mfma_f32_16x16x32_bf16 v[60:63], v[72:75], v[144:147], v[60:63]
	v_mfma_f32_16x16x32_bf16 v[56:59], v[84:87], v[144:147], v[56:59]
	v_mfma_f32_16x16x32_bf16 v[44:47], v[72:75], v[188:191], v[44:47]
	v_mfma_f32_16x16x32_bf16 v[40:43], v[84:87], v[188:191], v[40:43]
	v_mfma_f32_16x16x32_bf16 v[28:31], v[72:75], v[214:217], v[28:31]
	v_mfma_f32_16x16x32_bf16 v[24:27], v[84:87], v[214:217], v[24:27]
	v_mfma_f32_16x16x32_bf16 v[12:15], v[72:75], v[222:225], v[12:15]
	v_mfma_f32_16x16x32_bf16 v[8:11], v[84:87], v[222:225], v[8:11]
	v_mfma_f32_16x16x32_bf16 v[60:63], v[76:79], v[148:151], v[60:63]
	v_mfma_f32_16x16x32_bf16 v[56:59], v[92:95], v[148:151], v[56:59]
	v_mfma_f32_16x16x32_bf16 v[44:47], v[76:79], v[210:213], v[44:47]
	v_mfma_f32_16x16x32_bf16 v[40:43], v[92:95], v[210:213], v[40:43]
	v_mfma_f32_16x16x32_bf16 v[28:31], v[76:79], v[218:221], v[28:31]
	v_mfma_f32_16x16x32_bf16 v[24:27], v[92:95], v[218:221], v[24:27]
	v_mfma_f32_16x16x32_bf16 v[12:15], v[76:79], v[226:229], v[12:15]
	v_mfma_f32_16x16x32_bf16 v[8:11], v[92:95], v[226:229], v[8:11]
	s_barrier
	s_add_u32 s84, s38, 0x80000
	s_addc_u32 s85, s39, 0
	s_add_i32 s86, s86, s60
	s_mov_b32 m0, s86
	s_nop 0
	global_load_lds_dwordx4 v152, s[84:85]
	s_add_i32 m0, s86, 0x2000
	s_nop 0
	global_load_lds_dwordx4 v162, s[84:85]
	s_add_i32 s84, 0, 0x18000
	s_add_u32 s52, s52, 0x80000
	s_addc_u32 s53, s53, 0
	s_mov_b32 m0, s63
	s_waitcnt vmcnt(6)
	s_barrier
	v_mfma_f32_16x16x32_bf16 v[52:55], v[230:233], v[144:147], v[52:55]
	v_mfma_f32_16x16x32_bf16 v[48:51], v[238:241], v[144:147], v[48:51]
	v_mfma_f32_16x16x32_bf16 v[36:39], v[230:233], v[188:191], v[36:39]
	v_mfma_f32_16x16x32_bf16 v[32:35], v[238:241], v[188:191], v[32:35]
	v_mfma_f32_16x16x32_bf16 v[20:23], v[230:233], v[214:217], v[20:23]
	v_mfma_f32_16x16x32_bf16 v[16:19], v[238:241], v[214:217], v[16:19]
	v_mfma_f32_16x16x32_bf16 v[4:7], v[230:233], v[222:225], v[4:7]
	v_mfma_f32_16x16x32_bf16 v[0:3], v[238:241], v[222:225], v[0:3]
	v_mfma_f32_16x16x32_bf16 v[52:55], v[234:237], v[148:151], v[52:55]
	v_mfma_f32_16x16x32_bf16 v[48:51], v[242:245], v[148:151], v[48:51]
	v_mfma_f32_16x16x32_bf16 v[36:39], v[234:237], v[210:213], v[36:39]
	v_mfma_f32_16x16x32_bf16 v[32:35], v[242:245], v[210:213], v[32:35]
	v_mfma_f32_16x16x32_bf16 v[20:23], v[234:237], v[218:221], v[20:23]
	v_mfma_f32_16x16x32_bf16 v[16:19], v[242:245], v[218:221], v[16:19]
	v_mfma_f32_16x16x32_bf16 v[4:7], v[234:237], v[226:229], v[4:7]
	v_mfma_f32_16x16x32_bf16 v[0:3], v[242:245], v[226:229], v[0:3]
	s_barrier
	ds_read_b128 v[72:75], v248
	ds_read_b128 v[76:79], v248 offset:1024
	ds_read_b128 v[84:87], v248 offset:2048
	ds_read_b128 v[92:95], v248 offset:3072
	ds_read_b128 v[144:147], v208 offset:32768
	ds_read_b128 v[148:151], v208 offset:33792
	ds_read_b128 v[188:191], v208 offset:34816
	ds_read_b128 v[210:213], v208 offset:35840
	ds_read_b128 v[214:217], v208 offset:36864
	ds_read_b128 v[218:221], v208 offset:37888
	ds_read_b128 v[222:225], v208 offset:38912
	global_load_lds_dwordx4 v166, s[52:53]
	s_mov_b32 m0, s68
	ds_read_b128 v[226:229], v208 offset:39936
	global_load_lds_dwordx4 v164, s[52:53]
	s_waitcnt lgkmcnt(8)
	s_barrier
	s_waitcnt lgkmcnt(0)
	v_mfma_f32_16x16x32_bf16 v[140:143], v[72:75], v[144:147], v[140:143]
	v_mfma_f32_16x16x32_bf16 v[136:139], v[84:87], v[144:147], v[136:139]
	v_mfma_f32_16x16x32_bf16 v[124:127], v[72:75], v[188:191], v[124:127]
	v_mfma_f32_16x16x32_bf16 v[120:123], v[84:87], v[188:191], v[120:123]
	v_mfma_f32_16x16x32_bf16 v[108:111], v[72:75], v[214:217], v[108:111]
	v_mfma_f32_16x16x32_bf16 v[104:107], v[84:87], v[214:217], v[104:107]
	v_mfma_f32_16x16x32_bf16 v[88:91], v[72:75], v[222:225], v[88:91]
	v_mfma_f32_16x16x32_bf16 v[80:83], v[84:87], v[222:225], v[80:83]
	v_mfma_f32_16x16x32_bf16 v[140:143], v[76:79], v[148:151], v[140:143]
	v_mfma_f32_16x16x32_bf16 v[136:139], v[92:95], v[148:151], v[136:139]
	v_mfma_f32_16x16x32_bf16 v[124:127], v[76:79], v[210:213], v[124:127]
	v_mfma_f32_16x16x32_bf16 v[120:123], v[92:95], v[210:213], v[120:123]
	v_mfma_f32_16x16x32_bf16 v[108:111], v[76:79], v[218:221], v[108:111]
	v_mfma_f32_16x16x32_bf16 v[104:107], v[92:95], v[218:221], v[104:107]
	v_mfma_f32_16x16x32_bf16 v[88:91], v[76:79], v[226:229], v[88:91]
	v_mfma_f32_16x16x32_bf16 v[80:83], v[92:95], v[226:229], v[80:83]
	s_barrier
	s_add_i32 s52, 0, 0x1c000
	s_add_i32 s53, s84, s60
	s_add_u32 s100, s38, 0x80
	s_addc_u32 s101, s39, 0
	s_mov_b32 m0, s53
	ds_read_b128 v[230:233], v249
	ds_read_b128 v[234:237], v249 offset:1024
	ds_read_b128 v[238:241], v249 offset:2048
	global_load_lds_dwordx4 v152, s[100:101]
	s_add_i32 m0, s53, 0x2000
	ds_read_b128 v[242:245], v249 offset:3072
	global_load_lds_dwordx4 v162, s[100:101]
	s_barrier
	s_waitcnt lgkmcnt(0)
	v_mfma_f32_16x16x32_bf16 v[132:135], v[230:233], v[144:147], v[132:135]
	v_mfma_f32_16x16x32_bf16 v[128:131], v[238:241], v[144:147], v[128:131]
	v_mfma_f32_16x16x32_bf16 v[116:119], v[230:233], v[188:191], v[116:119]
	v_mfma_f32_16x16x32_bf16 v[112:115], v[238:241], v[188:191], v[112:115]
	v_mfma_f32_16x16x32_bf16 v[100:103], v[230:233], v[214:217], v[100:103]
	v_mfma_f32_16x16x32_bf16 v[96:99], v[238:241], v[214:217], v[96:99]
	v_mfma_f32_16x16x32_bf16 v[68:71], v[230:233], v[222:225], v[68:71]
	v_mfma_f32_16x16x32_bf16 v[64:67], v[238:241], v[222:225], v[64:67]
	v_mfma_f32_16x16x32_bf16 v[132:135], v[234:237], v[148:151], v[132:135]
	v_mfma_f32_16x16x32_bf16 v[128:131], v[242:245], v[148:151], v[128:131]
	v_mfma_f32_16x16x32_bf16 v[116:119], v[234:237], v[210:213], v[116:119]
	v_mfma_f32_16x16x32_bf16 v[112:115], v[242:245], v[210:213], v[112:115]
	v_mfma_f32_16x16x32_bf16 v[100:103], v[234:237], v[218:221], v[100:103]
	v_mfma_f32_16x16x32_bf16 v[96:99], v[242:245], v[218:221], v[96:99]
	v_mfma_f32_16x16x32_bf16 v[68:71], v[234:237], v[226:229], v[68:71]
	v_mfma_f32_16x16x32_bf16 v[64:67], v[242:245], v[226:229], v[64:67]
	s_barrier
	s_mov_b32 m0, s81
	ds_read_b128 v[144:147], v208 offset:49152
	ds_read_b128 v[148:151], v208 offset:50176
	ds_read_b128 v[188:191], v208 offset:51200
	ds_read_b128 v[210:213], v208 offset:52224
	ds_read_b128 v[214:217], v208 offset:53248
	ds_read_b128 v[218:221], v208 offset:54272
	ds_read_b128 v[222:225], v208 offset:55296
	global_load_lds_dwordx4 v166, s[98:99]
	s_mov_b32 m0, s82
	ds_read_b128 v[226:229], v208 offset:56320
	global_load_lds_dwordx4 v164, s[98:99]
	s_barrier
	s_waitcnt lgkmcnt(0)
	v_mfma_f32_16x16x32_bf16 v[60:63], v[72:75], v[144:147], v[60:63]
	v_mfma_f32_16x16x32_bf16 v[56:59], v[84:87], v[144:147], v[56:59]
	v_mfma_f32_16x16x32_bf16 v[44:47], v[72:75], v[188:191], v[44:47]
	v_mfma_f32_16x16x32_bf16 v[40:43], v[84:87], v[188:191], v[40:43]
	v_mfma_f32_16x16x32_bf16 v[28:31], v[72:75], v[214:217], v[28:31]
	v_mfma_f32_16x16x32_bf16 v[24:27], v[84:87], v[214:217], v[24:27]
	v_mfma_f32_16x16x32_bf16 v[12:15], v[72:75], v[222:225], v[12:15]
	v_mfma_f32_16x16x32_bf16 v[8:11], v[84:87], v[222:225], v[8:11]
	v_mfma_f32_16x16x32_bf16 v[60:63], v[76:79], v[148:151], v[60:63]
	v_mfma_f32_16x16x32_bf16 v[56:59], v[92:95], v[148:151], v[56:59]
	v_mfma_f32_16x16x32_bf16 v[44:47], v[76:79], v[210:213], v[44:47]
	v_mfma_f32_16x16x32_bf16 v[40:43], v[92:95], v[210:213], v[40:43]
	v_mfma_f32_16x16x32_bf16 v[28:31], v[76:79], v[218:221], v[28:31]
	v_mfma_f32_16x16x32_bf16 v[24:27], v[92:95], v[218:221], v[24:27]
	v_mfma_f32_16x16x32_bf16 v[12:15], v[76:79], v[226:229], v[12:15]
	v_mfma_f32_16x16x32_bf16 v[8:11], v[92:95], v[226:229], v[8:11]
	s_barrier
	s_add_u32 s38, s38, 0x80080
	s_addc_u32 s39, s39, 0
	s_add_i32 s52, s52, s60
	s_mov_b32 m0, s52
	s_nop 0
	global_load_lds_dwordx4 v152, s[38:39]
	s_add_i32 m0, s52, 0x2000
	s_nop 0
	global_load_lds_dwordx4 v162, s[38:39]
	s_add_i32 s30, s30, 2
	s_add_u32 s22, s22, 0x100
	s_addc_u32 s23, s23, 0
	s_add_u32 s17, s17, 0x100
	s_addc_u32 s21, s21, 0
	s_add_u32 s38, s22, 0xfff80080
	s_addc_u32 s39, s23, -1
	s_add_i32 s84, 0, 0x10000
	s_cmp_eq_u32 s30, 28
	s_cselect_b32 s53, s5, s39
	s_cselect_b32 s52, s6, s38
	s_cselect_b32 s39, s1, s21
	s_cselect_b32 s38, s7, s17
	s_add_i32 m0, s61, 0xc000
	s_cmp_gt_u32 s30, 29
	s_waitcnt vmcnt(6)
	s_barrier
	v_mfma_f32_16x16x32_bf16 v[52:55], v[230:233], v[144:147], v[52:55]
	v_mfma_f32_16x16x32_bf16 v[48:51], v[238:241], v[144:147], v[48:51]
	v_mfma_f32_16x16x32_bf16 v[36:39], v[230:233], v[188:191], v[36:39]
	v_mfma_f32_16x16x32_bf16 v[32:35], v[238:241], v[188:191], v[32:35]
	v_mfma_f32_16x16x32_bf16 v[20:23], v[230:233], v[214:217], v[20:23]
	v_mfma_f32_16x16x32_bf16 v[16:19], v[238:241], v[214:217], v[16:19]
	v_mfma_f32_16x16x32_bf16 v[4:7], v[230:233], v[222:225], v[4:7]
	v_mfma_f32_16x16x32_bf16 v[0:3], v[238:241], v[222:225], v[0:3]
	v_mfma_f32_16x16x32_bf16 v[52:55], v[234:237], v[148:151], v[52:55]
	v_mfma_f32_16x16x32_bf16 v[48:51], v[242:245], v[148:151], v[48:51]
	v_mfma_f32_16x16x32_bf16 v[36:39], v[234:237], v[210:213], v[36:39]
	v_mfma_f32_16x16x32_bf16 v[32:35], v[242:245], v[210:213], v[32:35]
	v_mfma_f32_16x16x32_bf16 v[20:23], v[234:237], v[218:221], v[20:23]
	v_mfma_f32_16x16x32_bf16 v[16:19], v[242:245], v[218:221], v[16:19]
	v_mfma_f32_16x16x32_bf16 v[4:7], v[234:237], v[226:229], v[4:7]
	v_mfma_f32_16x16x32_bf16 v[0:3], v[242:245], v[226:229], v[0:3]
	s_barrier
	s_cbranch_scc0 .LBB0_561
	s_cmpk_gt_u32 s15, 0xff
	s_cbranch_scc1 .Lal_e0_w
	s_barrier

.LBB0_773:
	ds_read_b128 v[144:147], v230
	ds_read_b128 v[148:151], v230 offset:1024
	ds_read_b128 v[162:165], v230 offset:2048
	ds_read_b128 v[166:169], v230 offset:3072
	ds_read_b128 v[170:173], v143
	ds_read_b128 v[174:177], v143 offset:1024
	ds_read_b128 v[178:181], v143 offset:2048
	ds_read_b128 v[182:185], v143 offset:3072
	ds_read_b128 v[186:189], v143 offset:4096
	ds_read_b128 v[190:193], v143 offset:5120
	ds_read_b128 v[206:209], v143 offset:6144
	global_load_lds_dwordx4 v134, s[20:21]
	s_add_i32 m0, s5, 0xe000
	ds_read_b128 v[210:213], v143 offset:7168
	global_load_lds_dwordx4 v136, s[20:21]
	s_waitcnt lgkmcnt(8)
	s_barrier
	s_waitcnt lgkmcnt(0)
	v_mfma_f32_16x16x32_bf16 v[124:127], v[144:147], v[170:173], v[124:127]
	v_mfma_f32_16x16x32_bf16 v[120:123], v[162:165], v[170:173], v[120:123]
	v_mfma_f32_16x16x32_bf16 v[108:111], v[144:147], v[178:181], v[108:111]
	v_mfma_f32_16x16x32_bf16 v[104:107], v[162:165], v[178:181], v[104:107]
	v_mfma_f32_16x16x32_bf16 v[92:95], v[144:147], v[186:189], v[92:95]
	v_mfma_f32_16x16x32_bf16 v[88:91], v[162:165], v[186:189], v[88:91]
	v_mfma_f32_16x16x32_bf16 v[76:79], v[144:147], v[206:209], v[76:79]
	v_mfma_f32_16x16x32_bf16 v[72:75], v[162:165], v[206:209], v[72:75]
	v_mfma_f32_16x16x32_bf16 v[124:127], v[148:151], v[174:177], v[124:127]
	v_mfma_f32_16x16x32_bf16 v[120:123], v[166:169], v[174:177], v[120:123]
	v_mfma_f32_16x16x32_bf16 v[108:111], v[148:151], v[182:185], v[108:111]
	v_mfma_f32_16x16x32_bf16 v[104:107], v[166:169], v[182:185], v[104:107]
	v_mfma_f32_16x16x32_bf16 v[92:95], v[148:151], v[190:193], v[92:95]
	v_mfma_f32_16x16x32_bf16 v[88:91], v[166:169], v[190:193], v[88:91]
	v_mfma_f32_16x16x32_bf16 v[76:79], v[148:151], v[210:213], v[76:79]
	v_mfma_f32_16x16x32_bf16 v[72:75], v[166:169], v[210:213], v[72:75]
	s_barrier
	s_add_i32 s68, 0, 0x14000
	s_add_i32 s61, s61, s4
	ds_read_b128 v[214:217], v231
	ds_read_b128 v[218:221], v231 offset:1024
	ds_read_b128 v[222:225], v231 offset:2048
	ds_read_b128 v[226:229], v231 offset:3072
	s_mov_b32 m0, s61
	s_nop 0
	global_load_lds_dwordx4 v152, s[22:23]
	s_add_i32 m0, s61, 0x2000
	s_nop 0
	global_load_lds_dwordx4 v132, s[22:23]
	s_barrier
	s_waitcnt lgkmcnt(0)
	v_mfma_f32_16x16x32_bf16 v[116:119], v[214:217], v[170:173], v[116:119]
	v_mfma_f32_16x16x32_bf16 v[112:115], v[222:225], v[170:173], v[112:115]
	v_mfma_f32_16x16x32_bf16 v[100:103], v[214:217], v[178:181], v[100:103]
	v_mfma_f32_16x16x32_bf16 v[96:99], v[222:225], v[178:181], v[96:99]
	v_mfma_f32_16x16x32_bf16 v[84:87], v[214:217], v[186:189], v[84:87]
	v_mfma_f32_16x16x32_bf16 v[80:83], v[222:225], v[186:189], v[80:83]
	v_mfma_f32_16x16x32_bf16 v[68:71], v[214:217], v[206:209], v[68:71]
	v_mfma_f32_16x16x32_bf16 v[64:67], v[222:225], v[206:209], v[64:67]
	v_mfma_f32_16x16x32_bf16 v[116:119], v[218:221], v[174:177], v[116:119]
	v_mfma_f32_16x16x32_bf16 v[112:115], v[226:229], v[174:177], v[112:115]
	v_mfma_f32_16x16x32_bf16 v[100:103], v[218:221], v[182:185], v[100:103]
	v_mfma_f32_16x16x32_bf16 v[96:99], v[226:229], v[182:185], v[96:99]
	v_mfma_f32_16x16x32_bf16 v[84:87], v[218:221], v[190:193], v[84:87]
	v_mfma_f32_16x16x32_bf16 v[80:83], v[226:229], v[190:193], v[80:83]
	v_mfma_f32_16x16x32_bf16 v[68:71], v[218:221], v[210:213], v[68:71]
	v_mfma_f32_16x16x32_bf16 v[64:67], v[226:229], v[210:213], v[64:67]
	s_barrier
	s_mov_b32 m0, s5
	s_add_u32 s98, s46, 0x80
	s_addc_u32 s99, s47, 0
	ds_read_b128 v[170:173], v143 offset:16384
	ds_read_b128 v[174:177], v143 offset:17408
	ds_read_b128 v[178:181], v143 offset:18432
	ds_read_b128 v[182:185], v143 offset:19456
	ds_read_b128 v[186:189], v143 offset:20480
	ds_read_b128 v[190:193], v143 offset:21504
	ds_read_b128 v[206:209], v143 offset:22528
	global_load_lds_dwordx4 v128, s[46:47]
	s_mov_b32 m0, s50
	ds_read_b128 v[210:213], v143 offset:23552
	global_load_lds_dwordx4 v130, s[46:47]
	s_barrier
	s_waitcnt lgkmcnt(0)
	v_mfma_f32_16x16x32_bf16 v[60:63], v[144:147], v[170:173], v[60:63]
	v_mfma_f32_16x16x32_bf16 v[56:59], v[162:165], v[170:173], v[56:59]
	v_mfma_f32_16x16x32_bf16 v[44:47], v[144:147], v[178:181], v[44:47]
	v_mfma_f32_16x16x32_bf16 v[40:43], v[162:165], v[178:181], v[40:43]
	v_mfma_f32_16x16x32_bf16 v[28:31], v[144:147], v[186:189], v[28:31]
	v_mfma_f32_16x16x32_bf16 v[24:27], v[162:165], v[186:189], v[24:27]
	v_mfma_f32_16x16x32_bf16 v[12:15], v[144:147], v[206:209], v[12:15]
	v_mfma_f32_16x16x32_bf16 v[8:11], v[162:165], v[206:209], v[8:11]
	v_mfma_f32_16x16x32_bf16 v[60:63], v[148:151], v[174:177], v[60:63]
	v_mfma_f32_16x16x32_bf16 v[56:59], v[166:169], v[174:177], v[56:59]
	v_mfma_f32_16x16x32_bf16 v[44:47], v[148:151], v[182:185], v[44:47]
	v_mfma_f32_16x16x32_bf16 v[40:43], v[166:169], v[182:185], v[40:43]
	v_mfma_f32_16x16x32_bf16 v[28:31], v[148:151], v[190:193], v[28:31]
	v_mfma_f32_16x16x32_bf16 v[24:27], v[166:169], v[190:193], v[24:27]
	v_mfma_f32_16x16x32_bf16 v[12:15], v[148:151], v[210:213], v[12:15]
	v_mfma_f32_16x16x32_bf16 v[8:11], v[166:169], v[210:213], v[8:11]
	s_barrier
	s_add_u32 s62, s22, 0x80000
	s_addc_u32 s63, s23, 0
	s_add_i32 s61, s68, s4
	s_mov_b32 m0, s61
	s_nop 0
	global_load_lds_dwordx4 v152, s[62:63]
	s_add_i32 m0, s61, 0x2000
	s_nop 0
	global_load_lds_dwordx4 v132, s[62:63]
	s_add_i32 s61, 0, 0x18000
	s_add_u32 s46, s46, 0x80000
	s_addc_u32 s47, s47, 0
	s_mov_b32 m0, s51
	s_waitcnt vmcnt(6)
	s_barrier
	v_mfma_f32_16x16x32_bf16 v[52:55], v[214:217], v[170:173], v[52:55]
	v_mfma_f32_16x16x32_bf16 v[48:51], v[222:225], v[170:173], v[48:51]
	v_mfma_f32_16x16x32_bf16 v[36:39], v[214:217], v[178:181], v[36:39]
	v_mfma_f32_16x16x32_bf16 v[32:35], v[222:225], v[178:181], v[32:35]
	v_mfma_f32_16x16x32_bf16 v[20:23], v[214:217], v[186:189], v[20:23]
	v_mfma_f32_16x16x32_bf16 v[16:19], v[222:225], v[186:189], v[16:19]
	v_mfma_f32_16x16x32_bf16 v[4:7], v[214:217], v[206:209], v[4:7]
	v_mfma_f32_16x16x32_bf16 v[0:3], v[222:225], v[206:209], v[0:3]
	v_mfma_f32_16x16x32_bf16 v[52:55], v[218:221], v[174:177], v[52:55]
	v_mfma_f32_16x16x32_bf16 v[48:51], v[226:229], v[174:177], v[48:51]
	v_mfma_f32_16x16x32_bf16 v[36:39], v[218:221], v[182:185], v[36:39]
	v_mfma_f32_16x16x32_bf16 v[32:35], v[226:229], v[182:185], v[32:35]
	v_mfma_f32_16x16x32_bf16 v[20:23], v[218:221], v[190:193], v[20:23]
	v_mfma_f32_16x16x32_bf16 v[16:19], v[226:229], v[190:193], v[16:19]
	v_mfma_f32_16x16x32_bf16 v[4:7], v[218:221], v[210:213], v[4:7]
	v_mfma_f32_16x16x32_bf16 v[0:3], v[226:229], v[210:213], v[0:3]
	s_barrier
	ds_read_b128 v[144:147], v232
	ds_read_b128 v[148:151], v232 offset:1024
	ds_read_b128 v[162:165], v232 offset:2048
	ds_read_b128 v[166:169], v232 offset:3072
	ds_read_b128 v[170:173], v143 offset:32768
	ds_read_b128 v[174:177], v143 offset:33792
	ds_read_b128 v[178:181], v143 offset:34816
	ds_read_b128 v[182:185], v143 offset:35840
	ds_read_b128 v[186:189], v143 offset:36864
	ds_read_b128 v[190:193], v143 offset:37888
	ds_read_b128 v[206:209], v143 offset:38912
	global_load_lds_dwordx4 v128, s[46:47]
	s_mov_b32 m0, s52
	ds_read_b128 v[210:213], v143 offset:39936
	global_load_lds_dwordx4 v130, s[46:47]
	s_waitcnt lgkmcnt(8)
	s_barrier
	s_waitcnt lgkmcnt(0)
	v_mfma_f32_16x16x32_bf16 v[124:127], v[144:147], v[170:173], v[124:127]
	v_mfma_f32_16x16x32_bf16 v[120:123], v[162:165], v[170:173], v[120:123]
	v_mfma_f32_16x16x32_bf16 v[108:111], v[144:147], v[178:181], v[108:111]
	v_mfma_f32_16x16x32_bf16 v[104:107], v[162:165], v[178:181], v[104:107]
	v_mfma_f32_16x16x32_bf16 v[92:95], v[144:147], v[186:189], v[92:95]
	v_mfma_f32_16x16x32_bf16 v[88:91], v[162:165], v[186:189], v[88:91]
	v_mfma_f32_16x16x32_bf16 v[76:79], v[144:147], v[206:209], v[76:79]
	v_mfma_f32_16x16x32_bf16 v[72:75], v[162:165], v[206:209], v[72:75]
	v_mfma_f32_16x16x32_bf16 v[124:127], v[148:151], v[174:177], v[124:127]
	v_mfma_f32_16x16x32_bf16 v[120:123], v[166:169], v[174:177], v[120:123]
	v_mfma_f32_16x16x32_bf16 v[108:111], v[148:151], v[182:185], v[108:111]
	v_mfma_f32_16x16x32_bf16 v[104:107], v[166:169], v[182:185], v[104:107]
	v_mfma_f32_16x16x32_bf16 v[92:95], v[148:151], v[190:193], v[92:95]
	v_mfma_f32_16x16x32_bf16 v[88:91], v[166:169], v[190:193], v[88:91]
	v_mfma_f32_16x16x32_bf16 v[76:79], v[148:151], v[210:213], v[76:79]
	v_mfma_f32_16x16x32_bf16 v[72:75], v[166:169], v[210:213], v[72:75]
	s_barrier
	s_add_i32 s46, 0, 0x1c000
	s_add_i32 s47, s61, s4
	s_add_u32 s100, s22, 0x80
	s_addc_u32 s101, s23, 0
	s_mov_b32 m0, s47
	ds_read_b128 v[214:217], v233
	ds_read_b128 v[218:221], v233 offset:1024
	ds_read_b128 v[222:225], v233 offset:2048
	global_load_lds_dwordx4 v152, s[100:101]
	s_add_i32 m0, s47, 0x2000
	ds_read_b128 v[226:229], v233 offset:3072
	global_load_lds_dwordx4 v132, s[100:101]
	s_barrier
	s_waitcnt lgkmcnt(0)
	v_mfma_f32_16x16x32_bf16 v[116:119], v[214:217], v[170:173], v[116:119]
	v_mfma_f32_16x16x32_bf16 v[112:115], v[222:225], v[170:173], v[112:115]
	v_mfma_f32_16x16x32_bf16 v[100:103], v[214:217], v[178:181], v[100:103]
	v_mfma_f32_16x16x32_bf16 v[96:99], v[222:225], v[178:181], v[96:99]
	v_mfma_f32_16x16x32_bf16 v[84:87], v[214:217], v[186:189], v[84:87]
	v_mfma_f32_16x16x32_bf16 v[80:83], v[222:225], v[186:189], v[80:83]
	v_mfma_f32_16x16x32_bf16 v[68:71], v[214:217], v[206:209], v[68:71]
	v_mfma_f32_16x16x32_bf16 v[64:67], v[222:225], v[206:209], v[64:67]
	v_mfma_f32_16x16x32_bf16 v[116:119], v[218:221], v[174:177], v[116:119]
	v_mfma_f32_16x16x32_bf16 v[112:115], v[226:229], v[174:177], v[112:115]
	v_mfma_f32_16x16x32_bf16 v[100:103], v[218:221], v[182:185], v[100:103]
	v_mfma_f32_16x16x32_bf16 v[96:99], v[226:229], v[182:185], v[96:99]
	v_mfma_f32_16x16x32_bf16 v[84:87], v[218:221], v[190:193], v[84:87]
	v_mfma_f32_16x16x32_bf16 v[80:83], v[226:229], v[190:193], v[80:83]
	v_mfma_f32_16x16x32_bf16 v[68:71], v[218:221], v[210:213], v[68:71]
	v_mfma_f32_16x16x32_bf16 v[64:67], v[226:229], v[210:213], v[64:67]
	s_barrier
	s_mov_b32 m0, s53
	ds_read_b128 v[170:173], v143 offset:49152
	ds_read_b128 v[174:177], v143 offset:50176
	ds_read_b128 v[178:181], v143 offset:51200
	ds_read_b128 v[182:185], v143 offset:52224
	ds_read_b128 v[186:189], v143 offset:53248
	ds_read_b128 v[190:193], v143 offset:54272
	ds_read_b128 v[206:209], v143 offset:55296
	global_load_lds_dwordx4 v128, s[98:99]
	s_mov_b32 m0, s54
	ds_read_b128 v[210:213], v143 offset:56320
	global_load_lds_dwordx4 v130, s[98:99]
	s_barrier
	s_waitcnt lgkmcnt(0)
	v_mfma_f32_16x16x32_bf16 v[60:63], v[144:147], v[170:173], v[60:63]
	v_mfma_f32_16x16x32_bf16 v[56:59], v[162:165], v[170:173], v[56:59]
	v_mfma_f32_16x16x32_bf16 v[44:47], v[144:147], v[178:181], v[44:47]
	v_mfma_f32_16x16x32_bf16 v[40:43], v[162:165], v[178:181], v[40:43]
	v_mfma_f32_16x16x32_bf16 v[28:31], v[144:147], v[186:189], v[28:31]
	v_mfma_f32_16x16x32_bf16 v[24:27], v[162:165], v[186:189], v[24:27]
	v_mfma_f32_16x16x32_bf16 v[12:15], v[144:147], v[206:209], v[12:15]
	v_mfma_f32_16x16x32_bf16 v[8:11], v[162:165], v[206:209], v[8:11]
	v_mfma_f32_16x16x32_bf16 v[60:63], v[148:151], v[174:177], v[60:63]
	v_mfma_f32_16x16x32_bf16 v[56:59], v[166:169], v[174:177], v[56:59]
	v_mfma_f32_16x16x32_bf16 v[44:47], v[148:151], v[182:185], v[44:47]
	v_mfma_f32_16x16x32_bf16 v[40:43], v[166:169], v[182:185], v[40:43]
	v_mfma_f32_16x16x32_bf16 v[28:31], v[148:151], v[190:193], v[28:31]
	v_mfma_f32_16x16x32_bf16 v[24:27], v[166:169], v[190:193], v[24:27]
	v_mfma_f32_16x16x32_bf16 v[12:15], v[148:151], v[210:213], v[12:15]
	v_mfma_f32_16x16x32_bf16 v[8:11], v[166:169], v[210:213], v[8:11]
	s_barrier
	s_add_u32 s22, s22, 0x80080
	s_addc_u32 s23, s23, 0
	s_add_i32 s46, s46, s4
	s_mov_b32 m0, s46
	s_nop 0
	global_load_lds_dwordx4 v152, s[22:23]
	s_add_i32 m0, s46, 0x2000
	s_nop 0
	global_load_lds_dwordx4 v132, s[22:23]
	s_add_i32 s60, s60, 2
	s_add_u32 s20, s20, 0x100
	s_addc_u32 s21, s21, 0
	s_add_u32 s58, s58, 0x100
	s_addc_u32 s59, s59, 0
	s_add_u32 s22, s20, 0xfff80080
	s_addc_u32 s23, s21, -1
	s_add_i32 s61, 0, 0x10000
	s_cmp_eq_u32 s60, 28
	s_cselect_b32 s47, s35, s23
	s_cselect_b32 s46, s56, s22
	s_cselect_b32 s23, s25, s59
	s_cselect_b32 s22, s57, s58
	s_add_i32 m0, s5, 0xc000
	s_cmp_gt_u32 s60, 29
	s_waitcnt vmcnt(6)
	s_barrier
	v_mfma_f32_16x16x32_bf16 v[52:55], v[214:217], v[170:173], v[52:55]
	v_mfma_f32_16x16x32_bf16 v[48:51], v[222:225], v[170:173], v[48:51]
	v_mfma_f32_16x16x32_bf16 v[36:39], v[214:217], v[178:181], v[36:39]
	v_mfma_f32_16x16x32_bf16 v[32:35], v[222:225], v[178:181], v[32:35]
	v_mfma_f32_16x16x32_bf16 v[20:23], v[214:217], v[186:189], v[20:23]
	v_mfma_f32_16x16x32_bf16 v[16:19], v[222:225], v[186:189], v[16:19]
	v_mfma_f32_16x16x32_bf16 v[4:7], v[214:217], v[206:209], v[4:7]
	v_mfma_f32_16x16x32_bf16 v[0:3], v[222:225], v[206:209], v[0:3]
	v_mfma_f32_16x16x32_bf16 v[52:55], v[218:221], v[174:177], v[52:55]
	v_mfma_f32_16x16x32_bf16 v[48:51], v[226:229], v[174:177], v[48:51]
	v_mfma_f32_16x16x32_bf16 v[36:39], v[218:221], v[182:185], v[36:39]
	v_mfma_f32_16x16x32_bf16 v[32:35], v[226:229], v[182:185], v[32:35]
	v_mfma_f32_16x16x32_bf16 v[20:23], v[218:221], v[190:193], v[20:23]
	v_mfma_f32_16x16x32_bf16 v[16:19], v[226:229], v[190:193], v[16:19]
	v_mfma_f32_16x16x32_bf16 v[4:7], v[218:221], v[210:213], v[4:7]
	v_mfma_f32_16x16x32_bf16 v[0:3], v[226:229], v[210:213], v[0:3]
	s_barrier
	s_cbranch_scc0 .LBB0_773
	s_cmpk_gt_u32 s14, 0xff
	s_cbranch_scc1 .Lal_e0_m
	s_barrier

.LBB0_836:
	ds_read_b128 v[120:123], v248
	ds_read_b128 v[124:127], v248 offset:1024
	ds_read_b128 v[132:135], v248 offset:2048
	ds_read_b128 v[136:139], v248 offset:3072
	ds_read_b128 v[186:189], v185
	ds_read_b128 v[190:193], v185 offset:1024
	ds_read_b128 v[206:209], v185 offset:2048
	ds_read_b128 v[210:213], v185 offset:3072
	ds_read_b128 v[214:217], v185 offset:4096
	ds_read_b128 v[218:221], v185 offset:5120
	ds_read_b128 v[222:225], v185 offset:6144
	global_load_lds_dwordx4 v176, s[20:21]
	s_add_i32 m0, s52, 0xe000
	ds_read_b128 v[226:229], v185 offset:7168
	global_load_lds_dwordx4 v178, s[20:21]
	s_waitcnt lgkmcnt(8)
	s_barrier
	s_waitcnt lgkmcnt(0)
	v_mfma_f32_16x16x32_bf16 v[140:143], v[120:123], v[186:189], v[140:143]
	v_mfma_f32_16x16x32_bf16 v[128:131], v[132:135], v[186:189], v[128:131]
	v_mfma_f32_16x16x32_bf16 v[112:115], v[120:123], v[206:209], v[112:115]
	v_mfma_f32_16x16x32_bf16 v[104:107], v[132:135], v[206:209], v[104:107]
	v_mfma_f32_16x16x32_bf16 v[96:99], v[120:123], v[214:217], v[96:99]
	v_mfma_f32_16x16x32_bf16 v[88:91], v[132:135], v[214:217], v[88:91]
	v_mfma_f32_16x16x32_bf16 v[80:83], v[120:123], v[222:225], v[80:83]
	v_mfma_f32_16x16x32_bf16 v[72:75], v[132:135], v[222:225], v[72:75]
	v_mfma_f32_16x16x32_bf16 v[140:143], v[124:127], v[190:193], v[140:143]
	v_mfma_f32_16x16x32_bf16 v[128:131], v[136:139], v[190:193], v[128:131]
	v_mfma_f32_16x16x32_bf16 v[112:115], v[124:127], v[210:213], v[112:115]
	v_mfma_f32_16x16x32_bf16 v[104:107], v[136:139], v[210:213], v[104:107]
	v_mfma_f32_16x16x32_bf16 v[96:99], v[124:127], v[218:221], v[96:99]
	v_mfma_f32_16x16x32_bf16 v[88:91], v[136:139], v[218:221], v[88:91]
	v_mfma_f32_16x16x32_bf16 v[80:83], v[124:127], v[226:229], v[80:83]
	v_mfma_f32_16x16x32_bf16 v[72:75], v[136:139], v[226:229], v[72:75]
	s_barrier
	s_add_i32 s80, 0, 0x14000
	s_add_i32 s78, s78, s51
	ds_read_b128 v[230:233], v249
	ds_read_b128 v[234:237], v249 offset:1024
	ds_read_b128 v[238:241], v249 offset:2048
	ds_read_b128 v[242:245], v249 offset:3072
	s_mov_b32 m0, s78
	s_nop 0
	global_load_lds_dwordx4 v152, s[22:23]
	s_add_i32 m0, s78, 0x2000
	s_nop 0
	global_load_lds_dwordx4 v144, s[22:23]
	s_barrier
	s_waitcnt lgkmcnt(0)
	v_mfma_f32_16x16x32_bf16 v[116:119], v[230:233], v[186:189], v[116:119]
	v_mfma_f32_16x16x32_bf16 v[108:111], v[238:241], v[186:189], v[108:111]
	v_mfma_f32_16x16x32_bf16 v[100:103], v[230:233], v[206:209], v[100:103]
	v_mfma_f32_16x16x32_bf16 v[92:95], v[238:241], v[206:209], v[92:95]
	v_mfma_f32_16x16x32_bf16 v[84:87], v[230:233], v[214:217], v[84:87]
	v_mfma_f32_16x16x32_bf16 v[76:79], v[238:241], v[214:217], v[76:79]
	v_mfma_f32_16x16x32_bf16 v[68:71], v[230:233], v[222:225], v[68:71]
	v_mfma_f32_16x16x32_bf16 v[64:67], v[238:241], v[222:225], v[64:67]
	v_mfma_f32_16x16x32_bf16 v[116:119], v[234:237], v[190:193], v[116:119]
	v_mfma_f32_16x16x32_bf16 v[108:111], v[242:245], v[190:193], v[108:111]
	v_mfma_f32_16x16x32_bf16 v[100:103], v[234:237], v[210:213], v[100:103]
	v_mfma_f32_16x16x32_bf16 v[92:95], v[242:245], v[210:213], v[92:95]
	v_mfma_f32_16x16x32_bf16 v[84:87], v[234:237], v[218:221], v[84:87]
	v_mfma_f32_16x16x32_bf16 v[76:79], v[242:245], v[218:221], v[76:79]
	v_mfma_f32_16x16x32_bf16 v[68:71], v[234:237], v[226:229], v[68:71]
	v_mfma_f32_16x16x32_bf16 v[64:67], v[242:245], v[226:229], v[64:67]
	s_barrier
	s_mov_b32 m0, s52
	s_add_u32 s98, s34, 0x80
	s_addc_u32 s99, s35, 0
	ds_read_b128 v[186:189], v185 offset:16384
	ds_read_b128 v[190:193], v185 offset:17408
	ds_read_b128 v[206:209], v185 offset:18432
	ds_read_b128 v[210:213], v185 offset:19456
	ds_read_b128 v[214:217], v185 offset:20480
	ds_read_b128 v[218:221], v185 offset:21504
	ds_read_b128 v[222:225], v185 offset:22528
	global_load_lds_dwordx4 v148, s[34:35]
	s_mov_b32 m0, s53
	ds_read_b128 v[226:229], v185 offset:23552
	global_load_lds_dwordx4 v146, s[34:35]
	s_barrier
	s_waitcnt lgkmcnt(0)
	v_mfma_f32_16x16x32_bf16 v[60:63], v[120:123], v[186:189], v[60:63]
	v_mfma_f32_16x16x32_bf16 v[56:59], v[132:135], v[186:189], v[56:59]
	v_mfma_f32_16x16x32_bf16 v[48:51], v[120:123], v[206:209], v[48:51]
	v_mfma_f32_16x16x32_bf16 v[40:43], v[132:135], v[206:209], v[40:43]
	v_mfma_f32_16x16x32_bf16 v[32:35], v[120:123], v[214:217], v[32:35]
	v_mfma_f32_16x16x32_bf16 v[24:27], v[132:135], v[214:217], v[24:27]
	v_mfma_f32_16x16x32_bf16 v[16:19], v[120:123], v[222:225], v[16:19]
	v_mfma_f32_16x16x32_bf16 v[8:11], v[132:135], v[222:225], v[8:11]
	v_mfma_f32_16x16x32_bf16 v[60:63], v[124:127], v[190:193], v[60:63]
	v_mfma_f32_16x16x32_bf16 v[56:59], v[136:139], v[190:193], v[56:59]
	v_mfma_f32_16x16x32_bf16 v[48:51], v[124:127], v[210:213], v[48:51]
	v_mfma_f32_16x16x32_bf16 v[40:43], v[136:139], v[210:213], v[40:43]
	v_mfma_f32_16x16x32_bf16 v[32:35], v[124:127], v[218:221], v[32:35]
	v_mfma_f32_16x16x32_bf16 v[24:27], v[136:139], v[218:221], v[24:27]
	v_mfma_f32_16x16x32_bf16 v[16:19], v[124:127], v[226:229], v[16:19]
	v_mfma_f32_16x16x32_bf16 v[8:11], v[136:139], v[226:229], v[8:11]
	s_barrier
	s_add_u32 s78, s22, 0x200000
	s_addc_u32 s79, s23, 0
	s_add_i32 s80, s80, s51
	s_mov_b32 m0, s80
	s_nop 0
	global_load_lds_dwordx4 v152, s[78:79]
	s_add_i32 m0, s80, 0x2000
	s_nop 0
	global_load_lds_dwordx4 v144, s[78:79]
	s_add_i32 s78, 0, 0x18000
	s_add_u32 s34, s34, 0x200000
	s_addc_u32 s35, s35, 0
	s_mov_b32 m0, s54
	s_waitcnt vmcnt(6)
	s_barrier
	v_mfma_f32_16x16x32_bf16 v[52:55], v[230:233], v[186:189], v[52:55]
	v_mfma_f32_16x16x32_bf16 v[44:47], v[238:241], v[186:189], v[44:47]
	v_mfma_f32_16x16x32_bf16 v[36:39], v[230:233], v[206:209], v[36:39]
	v_mfma_f32_16x16x32_bf16 v[28:31], v[238:241], v[206:209], v[28:31]
	v_mfma_f32_16x16x32_bf16 v[20:23], v[230:233], v[214:217], v[20:23]
	v_mfma_f32_16x16x32_bf16 v[12:15], v[238:241], v[214:217], v[12:15]
	v_mfma_f32_16x16x32_bf16 v[4:7], v[230:233], v[222:225], v[4:7]
	v_mfma_f32_16x16x32_bf16 v[0:3], v[238:241], v[222:225], v[0:3]
	v_mfma_f32_16x16x32_bf16 v[52:55], v[234:237], v[190:193], v[52:55]
	v_mfma_f32_16x16x32_bf16 v[44:47], v[242:245], v[190:193], v[44:47]
	v_mfma_f32_16x16x32_bf16 v[36:39], v[234:237], v[210:213], v[36:39]
	v_mfma_f32_16x16x32_bf16 v[28:31], v[242:245], v[210:213], v[28:31]
	v_mfma_f32_16x16x32_bf16 v[20:23], v[234:237], v[218:221], v[20:23]
	v_mfma_f32_16x16x32_bf16 v[12:15], v[242:245], v[218:221], v[12:15]
	v_mfma_f32_16x16x32_bf16 v[4:7], v[234:237], v[226:229], v[4:7]
	v_mfma_f32_16x16x32_bf16 v[0:3], v[242:245], v[226:229], v[0:3]
	s_barrier
	ds_read_b128 v[120:123], v250
	ds_read_b128 v[124:127], v250 offset:1024
	ds_read_b128 v[132:135], v250 offset:2048
	ds_read_b128 v[136:139], v250 offset:3072
	ds_read_b128 v[186:189], v185 offset:32768
	ds_read_b128 v[190:193], v185 offset:33792
	ds_read_b128 v[206:209], v185 offset:34816
	ds_read_b128 v[210:213], v185 offset:35840
	ds_read_b128 v[214:217], v185 offset:36864
	ds_read_b128 v[218:221], v185 offset:37888
	ds_read_b128 v[222:225], v185 offset:38912
	global_load_lds_dwordx4 v148, s[34:35]
	s_mov_b32 m0, s55
	ds_read_b128 v[226:229], v185 offset:39936
	global_load_lds_dwordx4 v146, s[34:35]
	s_waitcnt lgkmcnt(8)
	s_barrier
	s_waitcnt lgkmcnt(0)
	v_mfma_f32_16x16x32_bf16 v[140:143], v[120:123], v[186:189], v[140:143]
	v_mfma_f32_16x16x32_bf16 v[128:131], v[132:135], v[186:189], v[128:131]
	v_mfma_f32_16x16x32_bf16 v[112:115], v[120:123], v[206:209], v[112:115]
	v_mfma_f32_16x16x32_bf16 v[104:107], v[132:135], v[206:209], v[104:107]
	v_mfma_f32_16x16x32_bf16 v[96:99], v[120:123], v[214:217], v[96:99]
	v_mfma_f32_16x16x32_bf16 v[88:91], v[132:135], v[214:217], v[88:91]
	v_mfma_f32_16x16x32_bf16 v[80:83], v[120:123], v[222:225], v[80:83]
	v_mfma_f32_16x16x32_bf16 v[72:75], v[132:135], v[222:225], v[72:75]
	v_mfma_f32_16x16x32_bf16 v[140:143], v[124:127], v[190:193], v[140:143]
	v_mfma_f32_16x16x32_bf16 v[128:131], v[136:139], v[190:193], v[128:131]
	v_mfma_f32_16x16x32_bf16 v[112:115], v[124:127], v[210:213], v[112:115]
	v_mfma_f32_16x16x32_bf16 v[104:107], v[136:139], v[210:213], v[104:107]
	v_mfma_f32_16x16x32_bf16 v[96:99], v[124:127], v[218:221], v[96:99]
	v_mfma_f32_16x16x32_bf16 v[88:91], v[136:139], v[218:221], v[88:91]
	v_mfma_f32_16x16x32_bf16 v[80:83], v[124:127], v[226:229], v[80:83]
	v_mfma_f32_16x16x32_bf16 v[72:75], v[136:139], v[226:229], v[72:75]
	s_barrier
	s_add_i32 s34, 0, 0x1c000
	s_add_i32 s35, s78, s51
	s_add_u32 s100, s22, 0x80
	s_addc_u32 s101, s23, 0
	s_mov_b32 m0, s35
	ds_read_b128 v[230:233], v251
	ds_read_b128 v[234:237], v251 offset:1024
	ds_read_b128 v[238:241], v251 offset:2048
	global_load_lds_dwordx4 v152, s[100:101]
	s_add_i32 m0, s35, 0x2000
	ds_read_b128 v[242:245], v251 offset:3072
	global_load_lds_dwordx4 v144, s[100:101]
	s_barrier
	s_waitcnt lgkmcnt(0)
	v_mfma_f32_16x16x32_bf16 v[116:119], v[230:233], v[186:189], v[116:119]
	v_mfma_f32_16x16x32_bf16 v[108:111], v[238:241], v[186:189], v[108:111]
	v_mfma_f32_16x16x32_bf16 v[100:103], v[230:233], v[206:209], v[100:103]
	v_mfma_f32_16x16x32_bf16 v[92:95], v[238:241], v[206:209], v[92:95]
	v_mfma_f32_16x16x32_bf16 v[84:87], v[230:233], v[214:217], v[84:87]
	v_mfma_f32_16x16x32_bf16 v[76:79], v[238:241], v[214:217], v[76:79]
	v_mfma_f32_16x16x32_bf16 v[68:71], v[230:233], v[222:225], v[68:71]
	v_mfma_f32_16x16x32_bf16 v[64:67], v[238:241], v[222:225], v[64:67]
	v_mfma_f32_16x16x32_bf16 v[116:119], v[234:237], v[190:193], v[116:119]
	v_mfma_f32_16x16x32_bf16 v[108:111], v[242:245], v[190:193], v[108:111]
	v_mfma_f32_16x16x32_bf16 v[100:103], v[234:237], v[210:213], v[100:103]
	v_mfma_f32_16x16x32_bf16 v[92:95], v[242:245], v[210:213], v[92:95]
	v_mfma_f32_16x16x32_bf16 v[84:87], v[234:237], v[218:221], v[84:87]
	v_mfma_f32_16x16x32_bf16 v[76:79], v[242:245], v[218:221], v[76:79]
	v_mfma_f32_16x16x32_bf16 v[68:71], v[234:237], v[226:229], v[68:71]
	v_mfma_f32_16x16x32_bf16 v[64:67], v[242:245], v[226:229], v[64:67]
	s_barrier
	s_mov_b32 m0, s60
	ds_read_b128 v[186:189], v185 offset:49152
	ds_read_b128 v[190:193], v185 offset:50176
	ds_read_b128 v[206:209], v185 offset:51200
	ds_read_b128 v[210:213], v185 offset:52224
	ds_read_b128 v[214:217], v185 offset:53248
	ds_read_b128 v[218:221], v185 offset:54272
	ds_read_b128 v[222:225], v185 offset:55296
	global_load_lds_dwordx4 v148, s[98:99]
	s_mov_b32 m0, s61
	ds_read_b128 v[226:229], v185 offset:56320
	global_load_lds_dwordx4 v146, s[98:99]
	s_barrier
	s_waitcnt lgkmcnt(0)
	v_mfma_f32_16x16x32_bf16 v[60:63], v[120:123], v[186:189], v[60:63]
	v_mfma_f32_16x16x32_bf16 v[56:59], v[132:135], v[186:189], v[56:59]
	v_mfma_f32_16x16x32_bf16 v[48:51], v[120:123], v[206:209], v[48:51]
	v_mfma_f32_16x16x32_bf16 v[40:43], v[132:135], v[206:209], v[40:43]
	v_mfma_f32_16x16x32_bf16 v[32:35], v[120:123], v[214:217], v[32:35]
	v_mfma_f32_16x16x32_bf16 v[24:27], v[132:135], v[214:217], v[24:27]
	v_mfma_f32_16x16x32_bf16 v[16:19], v[120:123], v[222:225], v[16:19]
	v_mfma_f32_16x16x32_bf16 v[8:11], v[132:135], v[222:225], v[8:11]
	v_mfma_f32_16x16x32_bf16 v[60:63], v[124:127], v[190:193], v[60:63]
	v_mfma_f32_16x16x32_bf16 v[56:59], v[136:139], v[190:193], v[56:59]
	v_mfma_f32_16x16x32_bf16 v[48:51], v[124:127], v[210:213], v[48:51]
	v_mfma_f32_16x16x32_bf16 v[40:43], v[136:139], v[210:213], v[40:43]
	v_mfma_f32_16x16x32_bf16 v[32:35], v[124:127], v[218:221], v[32:35]
	v_mfma_f32_16x16x32_bf16 v[24:27], v[136:139], v[218:221], v[24:27]
	v_mfma_f32_16x16x32_bf16 v[16:19], v[124:127], v[226:229], v[16:19]
	v_mfma_f32_16x16x32_bf16 v[8:11], v[136:139], v[226:229], v[8:11]
	s_barrier
	s_add_u32 s22, s22, 0x200080
	s_addc_u32 s23, s23, 0
	s_add_i32 s34, s34, s51
	s_mov_b32 m0, s34
	s_nop 0
	global_load_lds_dwordx4 v152, s[22:23]
	s_add_i32 m0, s34, 0x2000
	s_nop 0
	global_load_lds_dwordx4 v144, s[22:23]
	s_add_i32 s69, s69, 2
	s_add_u32 s20, s20, 0x100
	s_addc_u32 s21, s21, 0
	s_add_u32 s63, s63, 0x100
	s_addc_u32 s68, s68, 0
	s_add_u32 s22, s20, 0xffe00080
	s_addc_u32 s23, s21, -1
	s_add_i32 s78, 0, 0x10000
	s_cmpk_eq_i32 s69, 0x7c
	s_cselect_b32 s35, s6, s23
	s_cselect_b32 s34, s7, s22
	s_cselect_b32 s23, s1, s68
	s_cselect_b32 s22, s17, s63
	s_add_i32 m0, s52, 0xc000
	s_cmpk_gt_u32 s69, 0x7d
	s_waitcnt vmcnt(6)
	s_barrier
	v_mfma_f32_16x16x32_bf16 v[52:55], v[230:233], v[186:189], v[52:55]
	v_mfma_f32_16x16x32_bf16 v[44:47], v[238:241], v[186:189], v[44:47]
	v_mfma_f32_16x16x32_bf16 v[36:39], v[230:233], v[206:209], v[36:39]
	v_mfma_f32_16x16x32_bf16 v[28:31], v[238:241], v[206:209], v[28:31]
	v_mfma_f32_16x16x32_bf16 v[20:23], v[230:233], v[214:217], v[20:23]
	v_mfma_f32_16x16x32_bf16 v[12:15], v[238:241], v[214:217], v[12:15]
	v_mfma_f32_16x16x32_bf16 v[4:7], v[230:233], v[222:225], v[4:7]
	v_mfma_f32_16x16x32_bf16 v[0:3], v[238:241], v[222:225], v[0:3]
	v_mfma_f32_16x16x32_bf16 v[52:55], v[234:237], v[190:193], v[52:55]
	v_mfma_f32_16x16x32_bf16 v[44:47], v[242:245], v[190:193], v[44:47]
	v_mfma_f32_16x16x32_bf16 v[36:39], v[234:237], v[210:213], v[36:39]
	v_mfma_f32_16x16x32_bf16 v[28:31], v[242:245], v[210:213], v[28:31]
	v_mfma_f32_16x16x32_bf16 v[20:23], v[234:237], v[218:221], v[20:23]
	v_mfma_f32_16x16x32_bf16 v[12:15], v[242:245], v[218:221], v[12:15]
	v_mfma_f32_16x16x32_bf16 v[4:7], v[234:237], v[226:229], v[4:7]
	v_mfma_f32_16x16x32_bf16 v[0:3], v[242:245], v[226:229], v[0:3]
	s_barrier
	s_cbranch_scc0 .LBB0_836
	s_cmpk_gt_u32 s42, 0xff
	s_cbranch_scc1 .Lal_e0_q
	s_barrier
